# gate/up GEMM: epilogues of the two wave halves no longer aligned (leading half's epilogue overlaps the trailing half's last MFMA block); barrier parity preserved
# baseline (speedup 1.0000x reference)
; #define PG8_STAGE(bufoff, gbase, voff) do { _Pragma("unroll") for (int _i = 0; _i < 2; ++_i) \
;         __builtin_amdgcn_global_load_lds((const unsigned*)((const char*)(gbase) + (voff)[_i]), (PG8_LAS unsigned*)(lds + (bufoff) + ldsw + _i * 8192), 16, 0, 0); } while (0)
; #define PG8_LDA(dst, b, h) do { _Pragma("unroll") for (int m = 0; m < 4; ++m) _Pragma("unroll") for (int k = 0; k < 2; ++k) dst[m][k] = *(const PG8_LAS bf16x8*)(lds + PG8_SA(b, h) + aoff + m * 2048 + k * 1024); } while (0)
; #define PG8_LDB(dst, b, h) do { _Pragma("unroll") for (int n = 0; n < 2; ++n) _Pragma("unroll") for (int k = 0; k < 2; ++k) dst[n][k] = *(const PG8_LAS bf16x8*)(lds + PG8_SB(b, h) + boff + n * 2048 + k * 1024); } while (0)
; #define PG8_MMA(ai, bj, At, Bt) do { __builtin_amdgcn_s_setprio(1); _Pragma("unroll") for (int m = 0; m < 4; ++m) _Pragma("unroll") for (int n = 0; n < 2; ++n) _Pragma("unroll") for (int k = 0; k < 2; ++k) \
;         acc[ai][bj][m][n] = __builtin_amdgcn_mfma_f32_16x16x32_bf16(Bt[n][k], At[m][k], acc[ai][bj][m][n], 0, 0, 0); __builtin_amdgcn_s_setprio(0); } while (0)
; #define PG8_WAIT_V(n) asm volatile("s_waitcnt vmcnt(" #n ")" ::: "memory")
; #define PG8_WAIT_L(n) asm volatile("s_waitcnt lgkmcnt(" #n ")" ::: "memory")
; #define PG8_BAR __builtin_amdgcn_s_barrier()
; #define PG8_SCHED __builtin_amdgcn_sched_barrier(0)
; template <class Epi, class Sched, bool ALIGN_EPI = false, bool SP2 = false>
; __device__ __forceinline__ void gemm_phase(PG8_LAS unsigned char* lds, const Gemm g, const Sched& S, const Epi& E) {
;     ...
;             PG8_LDB(B0, 0, 0); PG8_LDB(B1, 0, 1); PG8_SCHED; PG8_LDA(At, 0, 0); PG8_STAGE(PG8_SA(1, 1), a1 + hstep, voffA);
;             PG8_WAIT_V(8); PG8_WAIT_L(0); PG8_BAR; PG8_MMA(0, 0, At, B0); PG8_MMA(0, 1, At, B1); PG8_BAR; PG8_SCHED;
;             PG8_LDA(At, 0, 1); PG8_STAGE(PG8_SB(0, 0), b2, voffB); PG8_STAGE(PG8_SB(0, 1), b2 + hstep, voffB); PG8_STAGE(PG8_SA(0, 0), a2, voffA);
;             PG8_WAIT_V(8); PG8_WAIT_L(0); PG8_BAR; PG8_MMA(1, 0, At, B0); PG8_MMA(1, 1, At, B1); PG8_BAR; PG8_SCHED;
.LBB0_97:
	s_add_u32 s24, s22, 0xfffc0080
	s_addc_u32 s25, s23, -1
	s_add_i32 s52, 0, 0x10000
	s_cmp_eq_u32 vcc_lo, 12
	s_cselect_b32 s27, s17, s25
	s_cselect_b32 s26, s44, s24
	s_cselect_b32 s25, s15, s47
	s_cselect_b32 s24, s45, s46
	s_add_i32 s53, 0, 0x14000
	v_add_u32_e32 v152, s52, v175
	v_add_u32_e32 v162, s53, v175
	ds_read_b128 v[0:3], v152
	ds_read_b128 v[4:7], v152 offset:1024
	ds_read_b128 v[148:151], v152 offset:2048
	ds_read_b128 v[152:155], v152 offset:3072
	ds_read_b128 v[156:159], v162
	ds_read_b128 v[182:185], v162 offset:1024
	ds_read_b128 v[186:189], v162 offset:2048
	ds_read_b128 v[190:193], v162 offset:3072
	v_lshl_add_u64 v[176:177], s[22:23], 0, v[144:145]
	s_add_i32 m0, s65, 0xc000
	ds_read_b128 v[194:197], v180
	ds_read_b128 v[198:201], v180 offset:1024
	ds_read_b128 v[202:205], v180 offset:2048
	ds_read_b128 v[206:209], v180 offset:3072
	ds_read_b128 v[210:213], v180 offset:4096
	ds_read_b128 v[214:217], v180 offset:5120
	ds_read_b128 v[218:221], v180 offset:6144
	ds_read_b128 v[232:235], v180 offset:7168
	global_load_lds_dwordx4 v[176:177], off
	v_lshl_add_u64 v[176:177], s[22:23], 0, v[146:147]
	s_add_i32 m0, s65, 0xe000
	s_nop 0
	global_load_lds_dwordx4 v[176:177], off
	s_waitcnt vmcnt(8)
	s_waitcnt lgkmcnt(0)
	s_barrier
	s_setprio 1
	s_waitcnt lgkmcnt(0)
	v_mfma_f32_16x16x32_bf16 v[132:135], v[0:3], v[194:197], v[132:135]
	v_mfma_f32_16x16x32_bf16 v[124:127], v[148:151], v[194:197], v[124:127]
	v_mfma_f32_16x16x32_bf16 v[116:119], v[0:3], v[202:205], v[116:119]
	v_mfma_f32_16x16x32_bf16 v[108:111], v[148:151], v[202:205], v[108:111]
	v_mfma_f32_16x16x32_bf16 v[100:103], v[0:3], v[210:213], v[100:103]
	v_mfma_f32_16x16x32_bf16 v[92:95], v[148:151], v[210:213], v[92:95]
	v_mfma_f32_16x16x32_bf16 v[84:87], v[0:3], v[218:221], v[84:87]
	v_mfma_f32_16x16x32_bf16 v[76:79], v[148:151], v[218:221], v[76:79]
	v_mfma_f32_16x16x32_bf16 v[132:135], v[4:7], v[198:201], v[132:135]
	v_mfma_f32_16x16x32_bf16 v[124:127], v[152:155], v[198:201], v[124:127]
	v_mfma_f32_16x16x32_bf16 v[116:119], v[4:7], v[206:209], v[116:119]
	v_mfma_f32_16x16x32_bf16 v[108:111], v[152:155], v[206:209], v[108:111]
	v_mfma_f32_16x16x32_bf16 v[100:103], v[4:7], v[214:217], v[100:103]
	v_mfma_f32_16x16x32_bf16 v[92:95], v[152:155], v[214:217], v[92:95]
	v_mfma_f32_16x16x32_bf16 v[84:87], v[4:7], v[232:235], v[84:87]
	v_mfma_f32_16x16x32_bf16 v[76:79], v[152:155], v[232:235], v[76:79]
	s_setprio 0
	s_setprio 1
	v_mfma_f32_16x16x32_bf16 v[128:131], v[156:159], v[194:197], v[128:131]
	v_mfma_f32_16x16x32_bf16 v[120:123], v[186:189], v[194:197], v[120:123]
	v_mfma_f32_16x16x32_bf16 v[112:115], v[156:159], v[202:205], v[112:115]
	v_mfma_f32_16x16x32_bf16 v[104:107], v[186:189], v[202:205], v[104:107]
	v_mfma_f32_16x16x32_bf16 v[96:99], v[156:159], v[210:213], v[96:99]
	v_mfma_f32_16x16x32_bf16 v[88:91], v[186:189], v[210:213], v[88:91]
	v_mfma_f32_16x16x32_bf16 v[80:83], v[156:159], v[218:221], v[80:83]
	v_mfma_f32_16x16x32_bf16 v[72:75], v[186:189], v[218:221], v[72:75]
	v_mfma_f32_16x16x32_bf16 v[128:131], v[182:185], v[198:201], v[128:131]
	v_mfma_f32_16x16x32_bf16 v[120:123], v[190:193], v[198:201], v[120:123]
	v_mfma_f32_16x16x32_bf16 v[112:115], v[182:185], v[206:209], v[112:115]
	v_mfma_f32_16x16x32_bf16 v[104:107], v[190:193], v[206:209], v[104:107]
	v_mfma_f32_16x16x32_bf16 v[96:99], v[182:185], v[214:217], v[96:99]
	v_mfma_f32_16x16x32_bf16 v[88:91], v[190:193], v[214:217], v[88:91]
	v_mfma_f32_16x16x32_bf16 v[80:83], v[182:185], v[232:235], v[80:83]
	v_mfma_f32_16x16x32_bf16 v[72:75], v[190:193], v[232:235], v[72:75]
	s_setprio 0
	s_barrier
	s_add_i32 s52, s52, s29
	v_lshl_add_u64 v[176:177], s[24:25], 0, v[160:161]
	s_mov_b32 m0, s52
	ds_read_b128 v[194:197], v180 offset:16384
	ds_read_b128 v[198:201], v180 offset:17408
	ds_read_b128 v[202:205], v180 offset:18432
	ds_read_b128 v[206:209], v180 offset:19456
	ds_read_b128 v[210:213], v180 offset:20480
	ds_read_b128 v[214:217], v180 offset:21504
	ds_read_b128 v[218:221], v180 offset:22528
	ds_read_b128 v[232:235], v180 offset:23552
	global_load_lds_dwordx4 v[176:177], off
	s_add_i32 m0, s52, 0x2000
	s_add_u32 s68, s24, 0x40000
	v_lshl_add_u64 v[222:223], s[24:25], 0, v[136:137]
	s_addc_u32 s69, s25, 0
	s_add_i32 s52, s53, s29
	global_load_lds_dwordx4 v[222:223], off
	v_lshl_add_u64 v[236:237], s[68:69], 0, v[160:161]
	s_mov_b32 m0, s52
	v_lshl_add_u64 v[238:239], s[26:27], 0, v[138:139]
	global_load_lds_dwordx4 v[236:237], off
	v_lshl_add_u64 v[236:237], s[68:69], 0, v[136:137]
	s_add_i32 m0, s52, 0x2000
	s_nop 0
	global_load_lds_dwordx4 v[236:237], off
	v_lshl_add_u64 v[236:237], s[26:27], 0, v[140:141]
	s_mov_b32 m0, s65
	s_nop 0
	global_load_lds_dwordx4 v[236:237], off
	s_mov_b32 m0, s76
	s_nop 0
	global_load_lds_dwordx4 v[238:239], off
	s_waitcnt vmcnt(8)
	s_waitcnt lgkmcnt(0)
	s_barrier
; #define PG8_STAGE(bufoff, gbase, voff) do { _Pragma("unroll") for (int _i = 0; _i < 2; ++_i) \
;         __builtin_amdgcn_global_load_lds((const unsigned*)((const char*)(gbase) + (voff)[_i]), (PG8_LAS unsigned*)(lds + (bufoff) + ldsw + _i * 8192), 16, 0, 0); } while (0)
; #define PG8_LDA(dst, b, h) do { _Pragma("unroll") for (int m = 0; m < 4; ++m) _Pragma("unroll") for (int k = 0; k < 2; ++k) dst[m][k] = *(const PG8_LAS bf16x8*)(lds + PG8_SA(b, h) + aoff + m * 2048 + k * 1024); } while (0)
; #define PG8_LDB(dst, b, h) do { _Pragma("unroll") for (int n = 0; n < 2; ++n) _Pragma("unroll") for (int k = 0; k < 2; ++k) dst[n][k] = *(const PG8_LAS bf16x8*)(lds + PG8_SB(b, h) + boff + n * 2048 + k * 1024); } while (0)
; #define PG8_MMA(ai, bj, At, Bt) do { __builtin_amdgcn_s_setprio(1); _Pragma("unroll") for (int m = 0; m < 4; ++m) _Pragma("unroll") for (int n = 0; n < 2; ++n) _Pragma("unroll") for (int k = 0; k < 2; ++k) \
;         acc[ai][bj][m][n] = __builtin_amdgcn_mfma_f32_16x16x32_bf16(Bt[n][k], At[m][k], acc[ai][bj][m][n], 0, 0, 0); __builtin_amdgcn_s_setprio(0); } while (0)
; #define PG8_WAIT_V(n) asm volatile("s_waitcnt vmcnt(" #n ")" ::: "memory")
; #define PG8_WAIT_L(n) asm volatile("s_waitcnt lgkmcnt(" #n ")" ::: "memory")
; #define PG8_BAR __builtin_amdgcn_s_barrier()
; #define PG8_SCHED __builtin_amdgcn_sched_barrier(0)
; template <class Epi, class Sched, bool ALIGN_EPI = false, bool SP2 = false>
; __device__ __forceinline__ void gemm_phase(PG8_LAS unsigned char* lds, const Gemm g, const Sched& S, const Epi& E) {
;     ...
;             PG8_WAIT_V(8); PG8_WAIT_L(0); PG8_BAR; PG8_MMA(1, 0, At, B0); PG8_MMA(1, 1, At, B1); PG8_BAR; PG8_SCHED;
;             PG8_LDB(B0, 1, 0); PG8_LDB(B1, 1, 1); PG8_SCHED; PG8_LDA(At, 1, 0); PG8_STAGE(PG8_SA(0, 1), a2 + hstep, voffA);
;             PG8_WAIT_V(8); PG8_WAIT_L(0); PG8_BAR; PG8_MMA(0, 0, At, B0); PG8_MMA(0, 1, At, B1); PG8_BAR; PG8_SCHED;
;             PG8_LDA(At, 1, 1); PG8_STAGE(PG8_SB(1, 0), b3, voffB); PG8_STAGE(PG8_SB(1, 1), b3 + hstep, voffB); PG8_STAGE(PG8_SA(1, 0), a3, voffA);
	s_setprio 1
	s_waitcnt lgkmcnt(0)
	v_mfma_f32_16x16x32_bf16 v[68:71], v[0:3], v[194:197], v[68:71]
	v_mfma_f32_16x16x32_bf16 v[60:63], v[148:151], v[194:197], v[60:63]
	v_mfma_f32_16x16x32_bf16 v[52:55], v[0:3], v[202:205], v[52:55]
	v_mfma_f32_16x16x32_bf16 v[44:47], v[148:151], v[202:205], v[44:47]
	v_mfma_f32_16x16x32_bf16 v[36:39], v[0:3], v[210:213], v[36:39]
	v_mfma_f32_16x16x32_bf16 v[28:31], v[148:151], v[210:213], v[28:31]
	v_mfma_f32_16x16x32_bf16 v[0:3], v[0:3], v[218:221], v[20:23]
	v_mfma_f32_16x16x32_bf16 v[68:71], v[4:7], v[198:201], v[68:71]
	v_mfma_f32_16x16x32_bf16 v[60:63], v[152:155], v[198:201], v[60:63]
	v_mfma_f32_16x16x32_bf16 v[52:55], v[4:7], v[206:209], v[52:55]
	v_mfma_f32_16x16x32_bf16 v[44:47], v[152:155], v[206:209], v[44:47]
	v_mfma_f32_16x16x32_bf16 v[36:39], v[4:7], v[214:217], v[36:39]
	v_mfma_f32_16x16x32_bf16 v[28:31], v[152:155], v[214:217], v[28:31]
	v_mfma_f32_16x16x32_bf16 v[0:3], v[4:7], v[232:235], v[0:3]
	v_mfma_f32_16x16x32_bf16 v[4:7], v[148:151], v[218:221], v[12:15]
	v_mfma_f32_16x16x32_bf16 v[4:7], v[152:155], v[232:235], v[4:7]
	s_setprio 0
	s_setprio 1
	v_mfma_f32_16x16x32_bf16 v[12:15], v[156:159], v[194:197], v[64:67]
	v_mfma_f32_16x16x32_bf16 v[64:67], v[182:185], v[198:201], v[12:15]
	v_mfma_f32_16x16x32_bf16 v[12:15], v[186:189], v[194:197], v[56:59]
	v_mfma_f32_16x16x32_bf16 v[56:59], v[190:193], v[198:201], v[12:15]
	v_mfma_f32_16x16x32_bf16 v[12:15], v[156:159], v[202:205], v[48:51]
	v_mfma_f32_16x16x32_bf16 v[48:51], v[182:185], v[206:209], v[12:15]
	v_mfma_f32_16x16x32_bf16 v[12:15], v[186:189], v[202:205], v[40:43]
	v_mfma_f32_16x16x32_bf16 v[40:43], v[190:193], v[206:209], v[12:15]
	v_mfma_f32_16x16x32_bf16 v[12:15], v[156:159], v[210:213], v[32:35]
	v_mfma_f32_16x16x32_bf16 v[32:35], v[182:185], v[214:217], v[12:15]
	v_mfma_f32_16x16x32_bf16 v[12:15], v[186:189], v[210:213], v[24:27]
	v_mfma_f32_16x16x32_bf16 v[24:27], v[190:193], v[214:217], v[12:15]
	v_mfma_f32_16x16x32_bf16 v[12:15], v[156:159], v[218:221], v[16:19]
	v_mfma_f32_16x16x32_bf16 v[8:11], v[186:189], v[218:221], v[8:11]
	v_mfma_f32_16x16x32_bf16 v[16:19], v[182:185], v[232:235], v[12:15]
	v_mfma_f32_16x16x32_bf16 v[8:11], v[190:193], v[232:235], v[8:11]
	s_setprio 0
	s_barrier
	s_add_i32 s52, 0, 0x18000
	s_add_i32 s53, 0, 0x1c000
	v_add_u32_e32 v152, s52, v175
	v_add_u32_e32 v162, s53, v175
	ds_read_b128 v[12:15], v152
	ds_read_b128 v[20:23], v152 offset:1024
	ds_read_b128 v[148:151], v152 offset:2048
	ds_read_b128 v[152:155], v152 offset:3072
	ds_read_b128 v[156:159], v162
	ds_read_b128 v[182:185], v162 offset:1024
	ds_read_b128 v[186:189], v162 offset:2048
	ds_read_b128 v[190:193], v162 offset:3072
	s_add_u32 s26, s26, 0x40000
	s_addc_u32 s27, s27, 0
	s_mov_b32 m0, s86
	v_lshl_add_u64 v[240:241], s[26:27], 0, v[140:141]
	ds_read_b128 v[194:197], v180 offset:32768
	ds_read_b128 v[198:201], v180 offset:33792
	ds_read_b128 v[202:205], v180 offset:34816
	ds_read_b128 v[206:209], v180 offset:35840
	ds_read_b128 v[210:213], v180 offset:36864
	ds_read_b128 v[214:217], v180 offset:37888
	ds_read_b128 v[218:221], v180 offset:38912
	ds_read_b128 v[232:235], v180 offset:39936
	global_load_lds_dwordx4 v[240:241], off
	v_lshl_add_u64 v[240:241], s[26:27], 0, v[138:139]
	s_mov_b32 m0, s87
	s_nop 0
	global_load_lds_dwordx4 v[240:241], off
	s_waitcnt vmcnt(8)
	s_waitcnt lgkmcnt(0)
	s_barrier
	s_setprio 1
	s_waitcnt lgkmcnt(0)
	v_mfma_f32_16x16x32_bf16 v[132:135], v[12:15], v[194:197], v[132:135]
	v_mfma_f32_16x16x32_bf16 v[124:127], v[148:151], v[194:197], v[124:127]
	v_mfma_f32_16x16x32_bf16 v[116:119], v[12:15], v[202:205], v[116:119]
	v_mfma_f32_16x16x32_bf16 v[108:111], v[148:151], v[202:205], v[108:111]
	v_mfma_f32_16x16x32_bf16 v[100:103], v[12:15], v[210:213], v[100:103]
	v_mfma_f32_16x16x32_bf16 v[92:95], v[148:151], v[210:213], v[92:95]
	v_mfma_f32_16x16x32_bf16 v[84:87], v[12:15], v[218:221], v[84:87]
	v_mfma_f32_16x16x32_bf16 v[76:79], v[148:151], v[218:221], v[76:79]
	v_mfma_f32_16x16x32_bf16 v[132:135], v[20:23], v[198:201], v[132:135]
	v_mfma_f32_16x16x32_bf16 v[124:127], v[152:155], v[198:201], v[124:127]
	v_mfma_f32_16x16x32_bf16 v[116:119], v[20:23], v[206:209], v[116:119]
	v_mfma_f32_16x16x32_bf16 v[108:111], v[152:155], v[206:209], v[108:111]
	v_mfma_f32_16x16x32_bf16 v[100:103], v[20:23], v[214:217], v[100:103]
	v_mfma_f32_16x16x32_bf16 v[92:95], v[152:155], v[214:217], v[92:95]
	v_mfma_f32_16x16x32_bf16 v[84:87], v[20:23], v[232:235], v[84:87]
	v_mfma_f32_16x16x32_bf16 v[76:79], v[152:155], v[232:235], v[76:79]
	s_setprio 0
	s_setprio 1
	v_mfma_f32_16x16x32_bf16 v[128:131], v[156:159], v[194:197], v[128:131]
	v_mfma_f32_16x16x32_bf16 v[120:123], v[186:189], v[194:197], v[120:123]
	v_mfma_f32_16x16x32_bf16 v[112:115], v[156:159], v[202:205], v[112:115]
	v_mfma_f32_16x16x32_bf16 v[104:107], v[186:189], v[202:205], v[104:107]
	v_mfma_f32_16x16x32_bf16 v[96:99], v[156:159], v[210:213], v[96:99]
	v_mfma_f32_16x16x32_bf16 v[88:91], v[186:189], v[210:213], v[88:91]
	v_mfma_f32_16x16x32_bf16 v[80:83], v[156:159], v[218:221], v[80:83]
	v_mfma_f32_16x16x32_bf16 v[72:75], v[186:189], v[218:221], v[72:75]
	v_mfma_f32_16x16x32_bf16 v[128:131], v[182:185], v[198:201], v[128:131]
	v_mfma_f32_16x16x32_bf16 v[120:123], v[190:193], v[198:201], v[120:123]
	v_mfma_f32_16x16x32_bf16 v[112:115], v[182:185], v[206:209], v[112:115]
	v_mfma_f32_16x16x32_bf16 v[104:107], v[190:193], v[206:209], v[104:107]
	v_mfma_f32_16x16x32_bf16 v[96:99], v[182:185], v[214:217], v[96:99]
	v_mfma_f32_16x16x32_bf16 v[88:91], v[190:193], v[214:217], v[88:91]
	v_mfma_f32_16x16x32_bf16 v[80:83], v[182:185], v[232:235], v[80:83]
	v_mfma_f32_16x16x32_bf16 v[72:75], v[190:193], v[232:235], v[72:75]
	s_setprio 0
	s_barrier
; #define PG8_STAGE(bufoff, gbase, voff) do { _Pragma("unroll") for (int _i = 0; _i < 2; ++_i) \
;         __builtin_amdgcn_global_load_lds((const unsigned*)((const char*)(gbase) + (voff)[_i]), (PG8_LAS unsigned*)(lds + (bufoff) + ldsw + _i * 8192), 16, 0, 0); } while (0)
; #define PG8_LDA(dst, b, h) do { _Pragma("unroll") for (int m = 0; m < 4; ++m) _Pragma("unroll") for (int k = 0; k < 2; ++k) dst[m][k] = *(const PG8_LAS bf16x8*)(lds + PG8_SA(b, h) + aoff + m * 2048 + k * 1024); } while (0)
; #define PG8_MMA(ai, bj, At, Bt) do { __builtin_amdgcn_s_setprio(1); _Pragma("unroll") for (int m = 0; m < 4; ++m) _Pragma("unroll") for (int n = 0; n < 2; ++n) _Pragma("unroll") for (int k = 0; k < 2; ++k) \
;         acc[ai][bj][m][n] = __builtin_amdgcn_mfma_f32_16x16x32_bf16(Bt[n][k], At[m][k], acc[ai][bj][m][n], 0, 0, 0); __builtin_amdgcn_s_setprio(0); } while (0)
; #define PG8_WAIT_V(n) asm volatile("s_waitcnt vmcnt(" #n ")" ::: "memory")
; #define PG8_WAIT_L(n) asm volatile("s_waitcnt lgkmcnt(" #n ")" ::: "memory")
; #define PG8_BAR __builtin_amdgcn_s_barrier()
; #define PG8_SCHED __builtin_amdgcn_sched_barrier(0)
; template <class Epi, class Sched, bool ALIGN_EPI = false, bool SP2 = false>
; __device__ __forceinline__ void gemm_phase(PG8_LAS unsigned char* lds, const Gemm g, const Sched& S, const Epi& E) {
;     ...
;             PG8_LDA(At, 1, 1); PG8_STAGE(PG8_SB(1, 0), b3, voffB); PG8_STAGE(PG8_SB(1, 1), b3 + hstep, voffB); PG8_STAGE(PG8_SA(1, 0), a3, voffA);
;             PG8_WAIT_V(8); PG8_WAIT_L(0); PG8_BAR; PG8_MMA(1, 0, At, B0); PG8_MMA(1, 1, At, B1); PG8_BAR; PG8_SCHED;
;     ...
;         if constexpr (ALIGN_EPI) { if (wr == 0) PG8_BAR; }
	s_add_i32 s26, s52, s29
	v_lshl_add_u64 v[176:177], v[176:177], 0, s[50:51]
	s_mov_b32 m0, s26
	ds_read_b128 v[194:197], v180 offset:49152
	ds_read_b128 v[198:201], v180 offset:50176
	ds_read_b128 v[202:205], v180 offset:51200
	ds_read_b128 v[206:209], v180 offset:52224
	ds_read_b128 v[210:213], v180 offset:53248
	ds_read_b128 v[214:217], v180 offset:54272
	ds_read_b128 v[218:221], v180 offset:55296
	ds_read_b128 v[232:235], v180 offset:56320
	global_load_lds_dwordx4 v[176:177], off
	s_add_i32 m0, s26, 0x2000
	s_add_u32 s24, s24, 0x40080
	v_lshl_add_u64 v[176:177], v[222:223], 0, s[50:51]
	s_addc_u32 s25, s25, 0
	s_add_i32 s26, s53, s29
	global_load_lds_dwordx4 v[176:177], off
	v_lshl_add_u64 v[176:177], s[24:25], 0, v[160:161]
	s_mov_b32 m0, s26
	s_nop 0
	global_load_lds_dwordx4 v[176:177], off
	v_lshl_add_u64 v[176:177], s[24:25], 0, v[136:137]
	s_add_i32 m0, s26, 0x2000
	s_nop 0
	global_load_lds_dwordx4 v[176:177], off
	v_lshl_add_u64 v[176:177], v[236:237], 0, s[50:51]
	s_mov_b32 m0, s0
	s_nop 0
	global_load_lds_dwordx4 v[176:177], off
	v_lshl_add_u64 v[176:177], v[238:239], 0, s[50:51]
	s_mov_b32 m0, s40
	s_nop 0
	global_load_lds_dwordx4 v[176:177], off
	s_waitcnt vmcnt(8)
	s_waitcnt lgkmcnt(0)
	s_barrier
	s_setprio 1
	s_waitcnt lgkmcnt(0)
	v_mfma_f32_16x16x32_bf16 v[68:71], v[12:15], v[194:197], v[68:71]
	v_mfma_f32_16x16x32_bf16 v[52:55], v[12:15], v[202:205], v[52:55]
	v_mfma_f32_16x16x32_bf16 v[36:39], v[12:15], v[210:213], v[36:39]
	v_mfma_f32_16x16x32_bf16 v[0:3], v[12:15], v[218:221], v[0:3]
	v_mfma_f32_16x16x32_bf16 v[68:71], v[20:23], v[198:201], v[68:71]
	v_mfma_f32_16x16x32_bf16 v[60:63], v[148:151], v[194:197], v[60:63]
	v_mfma_f32_16x16x32_bf16 v[52:55], v[20:23], v[206:209], v[52:55]
	v_mfma_f32_16x16x32_bf16 v[44:47], v[148:151], v[202:205], v[44:47]
	v_mfma_f32_16x16x32_bf16 v[36:39], v[20:23], v[214:217], v[36:39]
	v_mfma_f32_16x16x32_bf16 v[28:31], v[148:151], v[210:213], v[28:31]
	v_mfma_f32_16x16x32_bf16 v[20:23], v[20:23], v[232:235], v[0:3]
	v_mfma_f32_16x16x32_bf16 v[0:3], v[148:151], v[218:221], v[4:7]
	v_mfma_f32_16x16x32_bf16 v[60:63], v[152:155], v[198:201], v[60:63]
	v_mfma_f32_16x16x32_bf16 v[44:47], v[152:155], v[206:209], v[44:47]
	v_mfma_f32_16x16x32_bf16 v[28:31], v[152:155], v[214:217], v[28:31]
	v_mfma_f32_16x16x32_bf16 v[12:15], v[152:155], v[232:235], v[0:3]
	s_setprio 0
	s_setprio 1
	v_mfma_f32_16x16x32_bf16 v[0:3], v[156:159], v[194:197], v[64:67]
	v_mfma_f32_16x16x32_bf16 v[64:67], v[182:185], v[198:201], v[0:3]
	v_mfma_f32_16x16x32_bf16 v[0:3], v[186:189], v[194:197], v[56:59]
	v_mfma_f32_16x16x32_bf16 v[56:59], v[190:193], v[198:201], v[0:3]
	v_mfma_f32_16x16x32_bf16 v[0:3], v[156:159], v[202:205], v[48:51]
	v_mfma_f32_16x16x32_bf16 v[48:51], v[182:185], v[206:209], v[0:3]
	v_mfma_f32_16x16x32_bf16 v[0:3], v[186:189], v[202:205], v[40:43]
	v_mfma_f32_16x16x32_bf16 v[40:43], v[190:193], v[206:209], v[0:3]
	v_mfma_f32_16x16x32_bf16 v[0:3], v[156:159], v[210:213], v[32:35]
	v_mfma_f32_16x16x32_bf16 v[32:35], v[182:185], v[214:217], v[0:3]
	v_mfma_f32_16x16x32_bf16 v[0:3], v[186:189], v[210:213], v[24:27]
	v_mfma_f32_16x16x32_bf16 v[24:27], v[190:193], v[214:217], v[0:3]
	v_mfma_f32_16x16x32_bf16 v[0:3], v[156:159], v[218:221], v[16:19]
	v_mfma_f32_16x16x32_bf16 v[16:19], v[182:185], v[232:235], v[0:3]
	v_mfma_f32_16x16x32_bf16 v[0:3], v[186:189], v[218:221], v[8:11]
	v_mfma_f32_16x16x32_bf16 v[8:11], v[190:193], v[232:235], v[0:3]
	s_setprio 0
	s_barrier
	s_add_i32 vcc_lo, vcc_lo, 2
	s_add_u32 s22, s22, 0x100
	s_addc_u32 s23, s23, 0
	s_add_u32 s46, s46, 0x100
	s_addc_u32 s47, s47, 0
	s_cmp_gt_u32 vcc_lo, 13
	s_cbranch_scc0 .LBB0_97
	s_and_b64 vcc, exec, s[12:13]
	s_cbranch_vccz .LBB0_100

; __device__ __forceinline__ unsigned cvt_pk_bf16(float lo, float hi) { unsigned r; asm volatile("v_cvt_pk_bf16_f32 %0, %1, %2" : "=v"(r) : "v"(lo), "v"(hi)); return r; }
;     __device__ __forceinline__ void operator()(const f32x4 (&acc)[2][2][4][2], const Unit& u, int wr, int wc, int fr, int fq) const {
;         const int row0 = u.pm * BM + wr * 64 + fr; const int col0 = u.pn * HALF + wc * 32 + 8 * fq;
;         float rs[8];
;         if (u.pm == pm0) {
; #pragma unroll
;             for (int i = 0; i < 8; ++i) rs[i] = tab[wr * 64 + fr + (i >> 2) * HALF + (i & 3) * 16]; }
;         else EPI_ROW_SCALES(rs, rowss, row0);
; #pragma unroll
;         for (int ai = 0; ai < 2; ++ai)
; #pragma unroll
;             for (int m = 0; m < 4; ++m) { const int row = row0 + ai * HALF + m * 16; const float r = rs[ai * 4 + m];
;                 float hv[8];
; #pragma unroll
;                 for (int n = 0; n < 2; ++n)
; #pragma unroll
;                     for (int e = 0; e < 4; ++e) { const float g = acc[ai][0][m][n][e] * r, up = acc[ai][1][m][n][e] * r;
;                         const float sg = g * __builtin_amdgcn_rcpf(1.0f + __builtin_amdgcn_exp2f(g * -1.4426950408889634f)); hv[n * 4 + e] = sg * up; }
;                 u32x4 w; w.x = cvt_pk_bf16(hv[0], hv[1]); w.y = cvt_pk_bf16(hv[2], hv[3]); w.z = cvt_pk_bf16(hv[4], hv[5]); w.w = cvt_pk_bf16(hv[6], hv[7]);
;                 *(u32x4*)(H + (size_t)row * 2816 + col0) = w; }
.LBB0_104:
	s_mov_b32 s100, 0xbfb8aa3b
	s_mov_b32 s101, 1.0
	s_waitcnt lgkmcnt(0)
	v_mov_b32_e32 v192, 0x16000
	v_mov_b32_e32 v193, 0
	v_mov_b32_e32 v194, 0x6e000
	v_mov_b32_e32 v195, 0
	v_pk_mul_f32 v[132:133], v[132:133], v[0:1] op_sel_hi:[1,0]
	v_pk_mul_f32 v[134:135], v[134:135], v[0:1] op_sel_hi:[1,0]
	v_pk_mul_f32 v[124:125], v[124:125], v[0:1] op_sel_hi:[1,0]
	v_pk_mul_f32 v[126:127], v[126:127], v[0:1] op_sel_hi:[1,0]
	v_pk_mul_f32 v[128:129], v[128:129], v[0:1] op_sel_hi:[1,0]
	v_pk_mul_f32 v[130:131], v[130:131], v[0:1] op_sel_hi:[1,0]
	v_pk_mul_f32 v[120:121], v[120:121], v[0:1] op_sel_hi:[1,0]
	v_pk_mul_f32 v[122:123], v[122:123], v[0:1] op_sel_hi:[1,0]
	v_pk_mul_f32 v[182:183], v[132:133], s[100:101] op_sel_hi:[1,0]
	v_pk_mul_f32 v[184:185], v[134:135], s[100:101] op_sel_hi:[1,0]
	v_pk_mul_f32 v[186:187], v[124:125], s[100:101] op_sel_hi:[1,0]
	v_pk_mul_f32 v[188:189], v[126:127], s[100:101] op_sel_hi:[1,0]
	v_exp_f32_e32 v182, v182
	v_exp_f32_e32 v183, v183
	v_exp_f32_e32 v184, v184
	v_exp_f32_e32 v185, v185
	v_exp_f32_e32 v186, v186
	v_exp_f32_e32 v187, v187
	v_exp_f32_e32 v188, v188
	v_exp_f32_e32 v189, v189
	v_pk_add_f32 v[182:183], v[182:183], s[100:101] op_sel:[0,1]
	v_pk_add_f32 v[184:185], v[184:185], s[100:101] op_sel:[0,1]
	v_pk_add_f32 v[186:187], v[186:187], s[100:101] op_sel:[0,1]
	v_pk_add_f32 v[188:189], v[188:189], s[100:101] op_sel:[0,1]
	v_rcp_f32_e32 v182, v182
	v_rcp_f32_e32 v183, v183
	v_rcp_f32_e32 v184, v184
	v_rcp_f32_e32 v185, v185
	v_rcp_f32_e32 v186, v186
	v_rcp_f32_e32 v187, v187
	v_rcp_f32_e32 v188, v188
	v_rcp_f32_e32 v189, v189
	v_pk_mul_f32 v[182:183], v[132:133], v[182:183]
	v_pk_mul_f32 v[184:185], v[134:135], v[184:185]
	v_pk_mul_f32 v[186:187], v[124:125], v[186:187]
	v_pk_mul_f32 v[188:189], v[126:127], v[188:189]
	v_pk_mul_f32 v[182:183], v[128:129], v[182:183]
	v_pk_mul_f32 v[184:185], v[130:131], v[184:185]
	v_pk_mul_f32 v[186:187], v[120:121], v[186:187]
	v_pk_mul_f32 v[188:189], v[122:123], v[188:189]
	v_cvt_pk_bf16_f32 v124, v182, v183
	v_cvt_pk_bf16_f32 v125, v184, v185
	v_cvt_pk_bf16_f32 v126, v186, v187
	v_cvt_pk_bf16_f32 v127, v188, v189
	v_lshl_or_b32 v176, s42, 7, v179
	v_ashrrev_i32_e32 v177, 31, v176
	s_andn2_b64 vcc, exec, s[4:5]
	v_mov_b64_e32 v[120:121], s[10:11]
	v_mad_u64_u32 v[128:129], s[22:23], v158, s91, v[120:121]
	v_mov_b32_e32 v122, v129
	v_mad_u64_u32 v[122:123], s[22:23], v159, s91, v[122:123]
	v_mov_b32_e32 v129, v122
	v_lshlrev_b64 v[122:123], 1, v[176:177]
	v_lshl_add_u64 v[128:129], v[128:129], 0, v[122:123]
	global_store_dwordx4 v[128:129], v[124:127], off
	s_nop 1
	v_pk_mul_f32 v[116:117], v[116:117], v[0:1] op_sel:[0,1]
	v_pk_mul_f32 v[118:119], v[118:119], v[0:1] op_sel:[0,1]
	v_pk_mul_f32 v[108:109], v[108:109], v[0:1] op_sel:[0,1]
	v_pk_mul_f32 v[110:111], v[110:111], v[0:1] op_sel:[0,1]
	v_pk_mul_f32 v[112:113], v[112:113], v[0:1] op_sel:[0,1]
	v_pk_mul_f32 v[114:115], v[114:115], v[0:1] op_sel:[0,1]
	v_pk_mul_f32 v[104:105], v[104:105], v[0:1] op_sel:[0,1]
	v_pk_mul_f32 v[106:107], v[106:107], v[0:1] op_sel:[0,1]
	v_pk_mul_f32 v[182:183], v[116:117], s[100:101] op_sel_hi:[1,0]
	v_pk_mul_f32 v[184:185], v[118:119], s[100:101] op_sel_hi:[1,0]
	v_pk_mul_f32 v[186:187], v[108:109], s[100:101] op_sel_hi:[1,0]
	v_pk_mul_f32 v[188:189], v[110:111], s[100:101] op_sel_hi:[1,0]
	v_exp_f32_e32 v182, v182
	v_exp_f32_e32 v183, v183
	v_exp_f32_e32 v184, v184
	v_exp_f32_e32 v185, v185
	v_exp_f32_e32 v186, v186
	v_exp_f32_e32 v187, v187
	v_exp_f32_e32 v188, v188
	v_exp_f32_e32 v189, v189
	v_pk_add_f32 v[182:183], v[182:183], s[100:101] op_sel:[0,1]
	v_pk_add_f32 v[184:185], v[184:185], s[100:101] op_sel:[0,1]
	v_pk_add_f32 v[186:187], v[186:187], s[100:101] op_sel:[0,1]
	v_pk_add_f32 v[188:189], v[188:189], s[100:101] op_sel:[0,1]
	v_rcp_f32_e32 v182, v182
	v_rcp_f32_e32 v183, v183
	v_rcp_f32_e32 v184, v184
	v_rcp_f32_e32 v185, v185
	v_rcp_f32_e32 v186, v186
	v_rcp_f32_e32 v187, v187
	v_rcp_f32_e32 v188, v188
	v_rcp_f32_e32 v189, v189
	v_pk_mul_f32 v[182:183], v[116:117], v[182:183]
	v_pk_mul_f32 v[184:185], v[118:119], v[184:185]
	v_pk_mul_f32 v[186:187], v[108:109], v[186:187]
	v_pk_mul_f32 v[188:189], v[110:111], v[188:189]
	v_pk_mul_f32 v[182:183], v[112:113], v[182:183]
	v_pk_mul_f32 v[184:185], v[114:115], v[184:185]
	v_pk_mul_f32 v[186:187], v[104:105], v[186:187]
	v_pk_mul_f32 v[188:189], v[106:107], v[188:189]
	v_cvt_pk_bf16_f32 v104, v182, v183
	v_cvt_pk_bf16_f32 v105, v184, v185
	v_cvt_pk_bf16_f32 v106, v186, v187
	v_cvt_pk_bf16_f32 v107, v188, v189
	v_lshl_add_u64 v[190:191], v[128:129], 0, v[192:193]
	global_store_dwordx4 v[190:191], v[104:107], off
	s_nop 1
	v_pk_mul_f32 v[100:101], v[100:101], v[2:3] op_sel_hi:[1,0]
	v_pk_mul_f32 v[102:103], v[102:103], v[2:3] op_sel_hi:[1,0]
	v_pk_mul_f32 v[92:93], v[92:93], v[2:3] op_sel_hi:[1,0]
	v_pk_mul_f32 v[94:95], v[94:95], v[2:3] op_sel_hi:[1,0]
	v_pk_mul_f32 v[96:97], v[96:97], v[2:3] op_sel_hi:[1,0]
	v_pk_mul_f32 v[98:99], v[98:99], v[2:3] op_sel_hi:[1,0]
	v_pk_mul_f32 v[88:89], v[88:89], v[2:3] op_sel_hi:[1,0]
	v_pk_mul_f32 v[90:91], v[90:91], v[2:3] op_sel_hi:[1,0]
	v_pk_mul_f32 v[182:183], v[100:101], s[100:101] op_sel_hi:[1,0]
	v_pk_mul_f32 v[184:185], v[102:103], s[100:101] op_sel_hi:[1,0]
	v_pk_mul_f32 v[186:187], v[92:93], s[100:101] op_sel_hi:[1,0]
	v_pk_mul_f32 v[188:189], v[94:95], s[100:101] op_sel_hi:[1,0]
	v_exp_f32_e32 v182, v182
	v_exp_f32_e32 v183, v183
	v_exp_f32_e32 v184, v184
	v_exp_f32_e32 v185, v185
	v_exp_f32_e32 v186, v186
	v_exp_f32_e32 v187, v187
	v_exp_f32_e32 v188, v188
	v_exp_f32_e32 v189, v189
	v_pk_add_f32 v[182:183], v[182:183], s[100:101] op_sel:[0,1]
; __device__ __forceinline__ unsigned cvt_pk_bf16(float lo, float hi) { unsigned r; asm volatile("v_cvt_pk_bf16_f32 %0, %1, %2" : "=v"(r) : "v"(lo), "v"(hi)); return r; }
;     __device__ __forceinline__ void operator()(const f32x4 (&acc)[2][2][4][2], const Unit& u, int wr, int wc, int fr, int fq) const {
;     ...
;             for (int m = 0; m < 4; ++m) { const int row = row0 + ai * HALF + m * 16; const float r = rs[ai * 4 + m];
;                 float hv[8];
; #pragma unroll
;                 for (int n = 0; n < 2; ++n)
; #pragma unroll
;                     for (int e = 0; e < 4; ++e) { const float g = acc[ai][0][m][n][e] * r, up = acc[ai][1][m][n][e] * r;
;                         const float sg = g * __builtin_amdgcn_rcpf(1.0f + __builtin_amdgcn_exp2f(g * -1.4426950408889634f)); hv[n * 4 + e] = sg * up; }
;                 u32x4 w; w.x = cvt_pk_bf16(hv[0], hv[1]); w.y = cvt_pk_bf16(hv[2], hv[3]); w.z = cvt_pk_bf16(hv[4], hv[5]); w.w = cvt_pk_bf16(hv[6], hv[7]);
;                 *(u32x4*)(H + (size_t)row * 2816 + col0) = w; }
	v_pk_add_f32 v[184:185], v[184:185], s[100:101] op_sel:[0,1]
	v_pk_add_f32 v[186:187], v[186:187], s[100:101] op_sel:[0,1]
	v_pk_add_f32 v[188:189], v[188:189], s[100:101] op_sel:[0,1]
	v_rcp_f32_e32 v182, v182
	v_rcp_f32_e32 v183, v183
	v_rcp_f32_e32 v184, v184
	v_rcp_f32_e32 v185, v185
	v_rcp_f32_e32 v186, v186
	v_rcp_f32_e32 v187, v187
	v_rcp_f32_e32 v188, v188
	v_rcp_f32_e32 v189, v189
	v_pk_mul_f32 v[182:183], v[100:101], v[182:183]
	v_pk_mul_f32 v[184:185], v[102:103], v[184:185]
	v_pk_mul_f32 v[186:187], v[92:93], v[186:187]
	v_pk_mul_f32 v[188:189], v[94:95], v[188:189]
	v_pk_mul_f32 v[182:183], v[96:97], v[182:183]
	v_pk_mul_f32 v[184:185], v[98:99], v[184:185]
	v_pk_mul_f32 v[186:187], v[88:89], v[186:187]
	v_pk_mul_f32 v[188:189], v[90:91], v[188:189]
	v_cvt_pk_bf16_f32 v88, v182, v183
	v_cvt_pk_bf16_f32 v89, v184, v185
	v_cvt_pk_bf16_f32 v90, v186, v187
	v_cvt_pk_bf16_f32 v91, v188, v189
	v_lshl_add_u64 v[190:191], v[190:191], 0, v[192:193]
	global_store_dwordx4 v[190:191], v[88:91], off
	s_nop 1
	v_pk_mul_f32 v[84:85], v[84:85], v[2:3] op_sel:[0,1]
	v_pk_mul_f32 v[86:87], v[86:87], v[2:3] op_sel:[0,1]
	v_pk_mul_f32 v[76:77], v[76:77], v[2:3] op_sel:[0,1]
	v_pk_mul_f32 v[78:79], v[78:79], v[2:3] op_sel:[0,1]
	v_pk_mul_f32 v[80:81], v[80:81], v[2:3] op_sel:[0,1]
	v_pk_mul_f32 v[82:83], v[82:83], v[2:3] op_sel:[0,1]
	v_pk_mul_f32 v[72:73], v[72:73], v[2:3] op_sel:[0,1]
	v_pk_mul_f32 v[74:75], v[74:75], v[2:3] op_sel:[0,1]
	v_pk_mul_f32 v[182:183], v[84:85], s[100:101] op_sel_hi:[1,0]
	v_pk_mul_f32 v[184:185], v[86:87], s[100:101] op_sel_hi:[1,0]
	v_pk_mul_f32 v[186:187], v[76:77], s[100:101] op_sel_hi:[1,0]
	v_pk_mul_f32 v[188:189], v[78:79], s[100:101] op_sel_hi:[1,0]
	v_exp_f32_e32 v182, v182
	v_exp_f32_e32 v183, v183
	v_exp_f32_e32 v184, v184
	v_exp_f32_e32 v185, v185
	v_exp_f32_e32 v186, v186
	v_exp_f32_e32 v187, v187
	v_exp_f32_e32 v188, v188
	v_exp_f32_e32 v189, v189
	v_pk_add_f32 v[182:183], v[182:183], s[100:101] op_sel:[0,1]
	v_pk_add_f32 v[184:185], v[184:185], s[100:101] op_sel:[0,1]
	v_pk_add_f32 v[186:187], v[186:187], s[100:101] op_sel:[0,1]
	v_pk_add_f32 v[188:189], v[188:189], s[100:101] op_sel:[0,1]
	v_rcp_f32_e32 v182, v182
	v_rcp_f32_e32 v183, v183
	v_rcp_f32_e32 v184, v184
	v_rcp_f32_e32 v185, v185
	v_rcp_f32_e32 v186, v186
	v_rcp_f32_e32 v187, v187
	v_rcp_f32_e32 v188, v188
	v_rcp_f32_e32 v189, v189
	v_pk_mul_f32 v[182:183], v[84:85], v[182:183]
	v_pk_mul_f32 v[184:185], v[86:87], v[184:185]
	v_pk_mul_f32 v[186:187], v[76:77], v[186:187]
	v_pk_mul_f32 v[188:189], v[78:79], v[188:189]
	v_pk_mul_f32 v[182:183], v[80:81], v[182:183]
	v_pk_mul_f32 v[184:185], v[82:83], v[184:185]
	v_pk_mul_f32 v[186:187], v[72:73], v[186:187]
	v_pk_mul_f32 v[188:189], v[74:75], v[188:189]
	v_cvt_pk_bf16_f32 v0, v182, v183
	v_cvt_pk_bf16_f32 v1, v184, v185
	v_cvt_pk_bf16_f32 v2, v186, v187
	v_cvt_pk_bf16_f32 v3, v188, v189
	v_lshl_add_u64 v[190:191], v[190:191], 0, v[192:193]
	global_store_dwordx4 v[190:191], v[0:3], off
	s_nop 1
	v_pk_mul_f32 v[68:69], v[68:69], v[4:5] op_sel_hi:[1,0]
	v_pk_mul_f32 v[70:71], v[70:71], v[4:5] op_sel_hi:[1,0]
	v_pk_mul_f32 v[60:61], v[60:61], v[4:5] op_sel_hi:[1,0]
	v_pk_mul_f32 v[62:63], v[62:63], v[4:5] op_sel_hi:[1,0]
	v_pk_mul_f32 v[64:65], v[64:65], v[4:5] op_sel_hi:[1,0]
	v_pk_mul_f32 v[66:67], v[66:67], v[4:5] op_sel_hi:[1,0]
	v_pk_mul_f32 v[56:57], v[56:57], v[4:5] op_sel_hi:[1,0]
	v_pk_mul_f32 v[58:59], v[58:59], v[4:5] op_sel_hi:[1,0]
	v_pk_mul_f32 v[182:183], v[68:69], s[100:101] op_sel_hi:[1,0]
	v_pk_mul_f32 v[184:185], v[70:71], s[100:101] op_sel_hi:[1,0]
	v_pk_mul_f32 v[186:187], v[60:61], s[100:101] op_sel_hi:[1,0]
	v_pk_mul_f32 v[188:189], v[62:63], s[100:101] op_sel_hi:[1,0]
	v_exp_f32_e32 v182, v182
	v_exp_f32_e32 v183, v183
	v_exp_f32_e32 v184, v184
	v_exp_f32_e32 v185, v185
	v_exp_f32_e32 v186, v186
	v_exp_f32_e32 v187, v187
	v_exp_f32_e32 v188, v188
	v_exp_f32_e32 v189, v189
	v_pk_add_f32 v[182:183], v[182:183], s[100:101] op_sel:[0,1]
	v_pk_add_f32 v[184:185], v[184:185], s[100:101] op_sel:[0,1]
	v_pk_add_f32 v[186:187], v[186:187], s[100:101] op_sel:[0,1]
	v_pk_add_f32 v[188:189], v[188:189], s[100:101] op_sel:[0,1]
	v_rcp_f32_e32 v182, v182
	v_rcp_f32_e32 v183, v183
	v_rcp_f32_e32 v184, v184
	v_rcp_f32_e32 v185, v185
	v_rcp_f32_e32 v186, v186
	v_rcp_f32_e32 v187, v187
	v_rcp_f32_e32 v188, v188
	v_rcp_f32_e32 v189, v189
	v_pk_mul_f32 v[182:183], v[68:69], v[182:183]
	v_pk_mul_f32 v[184:185], v[70:71], v[184:185]
	v_pk_mul_f32 v[186:187], v[60:61], v[186:187]
	v_pk_mul_f32 v[188:189], v[62:63], v[188:189]
	v_pk_mul_f32 v[182:183], v[64:65], v[182:183]
	v_pk_mul_f32 v[184:185], v[66:67], v[184:185]
	v_pk_mul_f32 v[186:187], v[56:57], v[186:187]
	v_pk_mul_f32 v[188:189], v[58:59], v[188:189]
	v_cvt_pk_bf16_f32 v0, v182, v183
	v_cvt_pk_bf16_f32 v1, v184, v185
	v_cvt_pk_bf16_f32 v2, v186, v187
	v_cvt_pk_bf16_f32 v3, v188, v189
	v_lshl_add_u64 v[190:191], v[190:191], 0, v[194:195]
	global_store_dwordx4 v[190:191], v[0:3], off
	s_nop 1
	v_pk_mul_f32 v[52:53], v[52:53], v[4:5] op_sel:[0,1]
	v_pk_mul_f32 v[54:55], v[54:55], v[4:5] op_sel:[0,1]
	v_pk_mul_f32 v[44:45], v[44:45], v[4:5] op_sel:[0,1]
	v_pk_mul_f32 v[46:47], v[46:47], v[4:5] op_sel:[0,1]
	v_pk_mul_f32 v[48:49], v[48:49], v[4:5] op_sel:[0,1]
	v_pk_mul_f32 v[50:51], v[50:51], v[4:5] op_sel:[0,1]
	v_pk_mul_f32 v[40:41], v[40:41], v[4:5] op_sel:[0,1]
	v_pk_mul_f32 v[42:43], v[42:43], v[4:5] op_sel:[0,1]
	v_pk_mul_f32 v[182:183], v[52:53], s[100:101] op_sel_hi:[1,0]
	v_pk_mul_f32 v[184:185], v[54:55], s[100:101] op_sel_hi:[1,0]
; __device__ __forceinline__ unsigned cvt_pk_bf16(float lo, float hi) { unsigned r; asm volatile("v_cvt_pk_bf16_f32 %0, %1, %2" : "=v"(r) : "v"(lo), "v"(hi)); return r; }
; #define PG8_BAR __builtin_amdgcn_s_barrier()
;     __device__ __forceinline__ void operator()(const f32x4 (&acc)[2][2][4][2], const Unit& u, int wr, int wc, int fr, int fq) const {
;     ...
;                     for (int e = 0; e < 4; ++e) { const float g = acc[ai][0][m][n][e] * r, up = acc[ai][1][m][n][e] * r;
;                         const float sg = g * __builtin_amdgcn_rcpf(1.0f + __builtin_amdgcn_exp2f(g * -1.4426950408889634f)); hv[n * 4 + e] = sg * up; }
;                 u32x4 w; w.x = cvt_pk_bf16(hv[0], hv[1]); w.y = cvt_pk_bf16(hv[2], hv[3]); w.z = cvt_pk_bf16(hv[4], hv[5]); w.w = cvt_pk_bf16(hv[6], hv[7]);
;                 *(u32x4*)(H + (size_t)row * 2816 + col0) = w; }
; template <class Epi, class Sched, bool ALIGN_EPI = false, bool SP2 = false>
; __device__ __forceinline__ void gemm_phase(PG8_LAS unsigned char* lds, const Gemm g, const Sched& S, const Epi& E) {
;     ...
;         if constexpr (ALIGN_EPI) { if (wr == 0) PG8_BAR; }
;         if constexpr (!Epi::AFTER_DRAIN) { E(acc, cur, wr, wc, fr, fq); S.done(cur); }
;         if (!has_next) break;
; #pragma unroll
;         for (int a = 0; a < 2; ++a)
; #pragma unroll
;             for (int b = 0; b < 2; ++b)
; #pragma unroll
;                 for (int m = 0; m < 4; ++m)
; #pragma unroll
;                     for (int n = 0; n < 2; ++n) acc[a][b][m][n] = (f32x4){0.f, 0.f, 0.f, 0.f};
;         cur = nxt; cA = nA; cB = nB; ++ui;
;         if constexpr (ALIGN_EPI) { if (wr == 1) PG8_BAR; }
	v_pk_mul_f32 v[186:187], v[44:45], s[100:101] op_sel_hi:[1,0]
	v_pk_mul_f32 v[188:189], v[46:47], s[100:101] op_sel_hi:[1,0]
	v_exp_f32_e32 v182, v182
	v_exp_f32_e32 v183, v183
	v_exp_f32_e32 v184, v184
	v_exp_f32_e32 v185, v185
	v_exp_f32_e32 v186, v186
	v_exp_f32_e32 v187, v187
	v_exp_f32_e32 v188, v188
	v_exp_f32_e32 v189, v189
	v_pk_add_f32 v[182:183], v[182:183], s[100:101] op_sel:[0,1]
	v_pk_add_f32 v[184:185], v[184:185], s[100:101] op_sel:[0,1]
	v_pk_add_f32 v[186:187], v[186:187], s[100:101] op_sel:[0,1]
	v_pk_add_f32 v[188:189], v[188:189], s[100:101] op_sel:[0,1]
	v_rcp_f32_e32 v182, v182
	v_rcp_f32_e32 v183, v183
	v_rcp_f32_e32 v184, v184
	v_rcp_f32_e32 v185, v185
	v_rcp_f32_e32 v186, v186
	v_rcp_f32_e32 v187, v187
	v_rcp_f32_e32 v188, v188
	v_rcp_f32_e32 v189, v189
	v_pk_mul_f32 v[182:183], v[52:53], v[182:183]
	v_pk_mul_f32 v[184:185], v[54:55], v[184:185]
	v_pk_mul_f32 v[186:187], v[44:45], v[186:187]
	v_pk_mul_f32 v[188:189], v[46:47], v[188:189]
	v_pk_mul_f32 v[182:183], v[48:49], v[182:183]
	v_pk_mul_f32 v[184:185], v[50:51], v[184:185]
	v_pk_mul_f32 v[186:187], v[40:41], v[186:187]
	v_pk_mul_f32 v[188:189], v[42:43], v[188:189]
	v_cvt_pk_bf16_f32 v0, v182, v183
	v_cvt_pk_bf16_f32 v1, v184, v185
	v_cvt_pk_bf16_f32 v2, v186, v187
	v_cvt_pk_bf16_f32 v3, v188, v189
	v_lshl_add_u64 v[190:191], v[190:191], 0, v[192:193]
	global_store_dwordx4 v[190:191], v[0:3], off
	s_nop 1
	v_pk_mul_f32 v[36:37], v[36:37], v[6:7] op_sel_hi:[1,0]
	v_pk_mul_f32 v[38:39], v[38:39], v[6:7] op_sel_hi:[1,0]
	v_pk_mul_f32 v[28:29], v[28:29], v[6:7] op_sel_hi:[1,0]
	v_pk_mul_f32 v[30:31], v[30:31], v[6:7] op_sel_hi:[1,0]
	v_pk_mul_f32 v[32:33], v[32:33], v[6:7] op_sel_hi:[1,0]
	v_pk_mul_f32 v[34:35], v[34:35], v[6:7] op_sel_hi:[1,0]
	v_pk_mul_f32 v[24:25], v[24:25], v[6:7] op_sel_hi:[1,0]
	v_pk_mul_f32 v[26:27], v[26:27], v[6:7] op_sel_hi:[1,0]
	v_pk_mul_f32 v[182:183], v[36:37], s[100:101] op_sel_hi:[1,0]
	v_pk_mul_f32 v[184:185], v[38:39], s[100:101] op_sel_hi:[1,0]
	v_pk_mul_f32 v[186:187], v[28:29], s[100:101] op_sel_hi:[1,0]
	v_pk_mul_f32 v[188:189], v[30:31], s[100:101] op_sel_hi:[1,0]
	v_exp_f32_e32 v182, v182
	v_exp_f32_e32 v183, v183
	v_exp_f32_e32 v184, v184
	v_exp_f32_e32 v185, v185
	v_exp_f32_e32 v186, v186
	v_exp_f32_e32 v187, v187
	v_exp_f32_e32 v188, v188
	v_exp_f32_e32 v189, v189
	v_pk_add_f32 v[182:183], v[182:183], s[100:101] op_sel:[0,1]
	v_pk_add_f32 v[184:185], v[184:185], s[100:101] op_sel:[0,1]
	v_pk_add_f32 v[186:187], v[186:187], s[100:101] op_sel:[0,1]
	v_pk_add_f32 v[188:189], v[188:189], s[100:101] op_sel:[0,1]
	v_rcp_f32_e32 v182, v182
	v_rcp_f32_e32 v183, v183
	v_rcp_f32_e32 v184, v184
	v_rcp_f32_e32 v185, v185
	v_rcp_f32_e32 v186, v186
	v_rcp_f32_e32 v187, v187
	v_rcp_f32_e32 v188, v188
	v_rcp_f32_e32 v189, v189
	v_pk_mul_f32 v[182:183], v[36:37], v[182:183]
	v_pk_mul_f32 v[184:185], v[38:39], v[184:185]
	v_pk_mul_f32 v[186:187], v[28:29], v[186:187]
	v_pk_mul_f32 v[188:189], v[30:31], v[188:189]
	v_pk_mul_f32 v[182:183], v[32:33], v[182:183]
	v_pk_mul_f32 v[184:185], v[34:35], v[184:185]
	v_pk_mul_f32 v[186:187], v[24:25], v[186:187]
	v_pk_mul_f32 v[188:189], v[26:27], v[188:189]
	v_cvt_pk_bf16_f32 v0, v182, v183
	v_cvt_pk_bf16_f32 v1, v184, v185
	v_cvt_pk_bf16_f32 v2, v186, v187
	v_cvt_pk_bf16_f32 v3, v188, v189
	v_lshl_add_u64 v[190:191], v[190:191], 0, v[192:193]
	global_store_dwordx4 v[190:191], v[0:3], off
	s_nop 1
	v_pk_mul_f32 v[20:21], v[20:21], v[6:7] op_sel:[0,1]
	v_pk_mul_f32 v[22:23], v[22:23], v[6:7] op_sel:[0,1]
	v_pk_mul_f32 v[12:13], v[12:13], v[6:7] op_sel:[0,1]
	v_pk_mul_f32 v[14:15], v[14:15], v[6:7] op_sel:[0,1]
	v_pk_mul_f32 v[16:17], v[16:17], v[6:7] op_sel:[0,1]
	v_pk_mul_f32 v[18:19], v[18:19], v[6:7] op_sel:[0,1]
	v_pk_mul_f32 v[8:9], v[8:9], v[6:7] op_sel:[0,1]
	v_pk_mul_f32 v[10:11], v[10:11], v[6:7] op_sel:[0,1]
	v_pk_mul_f32 v[182:183], v[20:21], s[100:101] op_sel_hi:[1,0]
	v_pk_mul_f32 v[184:185], v[22:23], s[100:101] op_sel_hi:[1,0]
	v_pk_mul_f32 v[186:187], v[12:13], s[100:101] op_sel_hi:[1,0]
	v_pk_mul_f32 v[188:189], v[14:15], s[100:101] op_sel_hi:[1,0]
	v_exp_f32_e32 v182, v182
	v_exp_f32_e32 v183, v183
	v_exp_f32_e32 v184, v184
	v_exp_f32_e32 v185, v185
	v_exp_f32_e32 v186, v186
	v_exp_f32_e32 v187, v187
	v_exp_f32_e32 v188, v188
	v_exp_f32_e32 v189, v189
	v_pk_add_f32 v[182:183], v[182:183], s[100:101] op_sel:[0,1]
	v_pk_add_f32 v[184:185], v[184:185], s[100:101] op_sel:[0,1]
	v_pk_add_f32 v[186:187], v[186:187], s[100:101] op_sel:[0,1]
	v_pk_add_f32 v[188:189], v[188:189], s[100:101] op_sel:[0,1]
	v_rcp_f32_e32 v182, v182
	v_rcp_f32_e32 v183, v183
	v_rcp_f32_e32 v184, v184
	v_rcp_f32_e32 v185, v185
	v_rcp_f32_e32 v186, v186
	v_rcp_f32_e32 v187, v187
	v_rcp_f32_e32 v188, v188
	v_rcp_f32_e32 v189, v189
	v_pk_mul_f32 v[182:183], v[20:21], v[182:183]
	v_pk_mul_f32 v[184:185], v[22:23], v[184:185]
	v_pk_mul_f32 v[186:187], v[12:13], v[186:187]
	v_pk_mul_f32 v[188:189], v[14:15], v[188:189]
	v_pk_mul_f32 v[182:183], v[16:17], v[182:183]
	v_pk_mul_f32 v[184:185], v[18:19], v[184:185]
	v_pk_mul_f32 v[186:187], v[8:9], v[186:187]
	v_pk_mul_f32 v[188:189], v[10:11], v[188:189]
	v_cvt_pk_bf16_f32 v0, v182, v183
	v_cvt_pk_bf16_f32 v1, v184, v185
	v_cvt_pk_bf16_f32 v2, v186, v187
	v_cvt_pk_bf16_f32 v3, v188, v189
	v_lshl_add_u64 v[190:191], v[190:191], 0, v[192:193]
	s_mov_b64 s[22:23], -1
	global_store_dwordx4 v[190:191], v[0:3], off
	s_nop 1
	s_cbranch_vccnz .LBB0_93
	s_andn2_b64 vcc, exec, s[8:9]
	s_cbranch_vccnz .LBB0_92
	s_branch .LBB0_92
.LBB0_107:
	s_and_b64 vcc, exec, s[12:13]
	s_cbranch_vccz .Lgu_noextra
	s_barrier
